# PB: tile loops compute the current tile's LDS fragment base address before the iteration barrier (first fragment read issues right behind the barrier)
# speedup vs baseline: 1.0061x; 1.0061x over previous
.LBB0_667:
	s_mulk_i32 s6, 0x4a00
	v_lshl_or_b32 v0, v141, 2, s6
	v_add3_u32 v14, s6, v144, v118
	s_cmp_gt_i32 s86, s15
	s_waitcnt lgkmcnt(0)
	s_barrier
	s_cbranch_scc1 .Ld5f_inactive
	ds_read_b128 v[2:5], v0 offset:18528
	ds_read_b128 v[6:9], v0 offset:18496
	ds_read_b128 v[10:13], v0 offset:18464
	ds_read_b128 v[48:51], v0 offset:18432
	s_waitcnt lgkmcnt(3)
	v_pk_add_f32 v[60:61], v[136:137], v[2:3] op_sel_hi:[0,1]
	v_pk_add_f32 v[62:63], v[136:137], v[4:5] op_sel_hi:[0,1]
	ds_read_b128 v[2:5], v14
	s_waitcnt lgkmcnt(3)
	v_pk_add_f32 v[56:57], v[136:137], v[6:7] op_sel_hi:[0,1]
	s_waitcnt lgkmcnt(2)
	v_pk_add_f32 v[52:53], v[136:137], v[10:11] op_sel_hi:[0,1]
	s_waitcnt lgkmcnt(1)
	v_pk_add_f32 v[48:49], v[136:137], v[48:49] op_sel_hi:[0,1]
	v_pk_add_f32 v[58:59], v[136:137], v[8:9] op_sel_hi:[0,1]
	v_pk_add_f32 v[54:55], v[136:137], v[12:13] op_sel_hi:[0,1]
	v_pk_add_f32 v[50:51], v[136:137], v[50:51] op_sel_hi:[0,1]
	ds_read_b128 v[6:9], v0 offset:18656
	ds_read_b128 v[10:13], v0 offset:18560
	ds_read_b128 v[64:67], v0 offset:18624
	ds_read_b128 v[68:71], v0 offset:18592
	ds_read_b128 v[150:153], v14 offset:4608
	s_waitcnt lgkmcnt(5)
	v_mfma_f32_32x32x16_bf16 v[48:63], v[2:5], v[80:83], v[48:63]
	ds_read_b128 v[2:5], v14 offset:32
	ds_read_b128 v[236:239], v14 offset:4640
	ds_read_b128 v[240:243], v14 offset:64
	ds_read_b128 v[244:247], v14 offset:4672
	ds_read_b128 v[248:251], v14 offset:96
	s_waitcnt lgkmcnt(9)
	v_add_f32_e64 v76, v136, v6
	v_add_f32_e64 v77, v136, v7
	s_waitcnt lgkmcnt(7)
	v_pk_add_f32 v[72:73], v[136:137], v[64:65] op_sel_hi:[0,1]
	s_waitcnt lgkmcnt(6)
	v_pk_add_f32 v[68:69], v[136:137], v[68:69] op_sel_hi:[0,1]
	v_pk_add_f32 v[64:65], v[136:137], v[10:11] op_sel_hi:[0,1]
	v_pk_add_f32 v[78:79], v[136:137], v[8:9] op_sel_hi:[0,1]
	v_pk_add_f32 v[74:75], v[136:137], v[66:67] op_sel_hi:[0,1]
	v_pk_add_f32 v[70:71], v[136:137], v[70:71] op_sel_hi:[0,1]
	v_pk_add_f32 v[66:67], v[136:137], v[12:13] op_sel_hi:[0,1]
	s_waitcnt lgkmcnt(4)
	v_mfma_f32_32x32x16_bf16 v[48:63], v[2:5], v[84:87], v[48:63]
	ds_read_b128 v[2:5], v14 offset:4704
	s_add_i32 s0, s86, 63
	v_cmp_le_i32_e32 vcc, s0, v116
	s_cmp_eq_u64 vcc, exec
	v_mfma_f32_32x32x16_bf16 v[64:79], v[150:153], v[80:83], v[64:79]
	s_waitcnt lgkmcnt(4)
	v_mfma_f32_32x32x16_bf16 v[64:79], v[236:239], v[84:87], v[64:79]
	s_waitcnt lgkmcnt(3)
	v_mfma_f32_32x32x16_bf16 v[48:63], v[240:243], v[88:91], v[48:63]
	s_waitcnt lgkmcnt(2)
	v_mfma_f32_32x32x16_bf16 v[64:79], v[244:247], v[88:91], v[64:79]
	s_waitcnt lgkmcnt(1)
	v_mfma_f32_32x32x16_bf16 v[48:63], v[248:251], v[92:95], v[48:63]
	s_waitcnt lgkmcnt(0)
	v_mfma_f32_32x32x16_bf16 v[64:79], v[2:5], v[92:95], v[64:79]
	s_cbranch_scc1 .LBB0_672
	v_add_u32_e32 v0, s86, v141
	v_cmp_lt_i32_e32 vcc, v0, v116
	v_add_u32_e32 v2, 2, v0
	s_nop 4
	v_cndmask_b32_e32 v49, v169, v49, vcc
	v_cmp_le_i32_e32 vcc, v0, v116
	s_nop 1
	v_cndmask_b32_e32 v48, v169, v48, vcc
	v_cmp_le_i32_e32 vcc, v2, v116
	v_add_u32_e32 v2, 3, v0
	s_nop 0
	v_cndmask_b32_e32 v50, v169, v50, vcc
	v_cmp_le_i32_e32 vcc, v2, v116
	v_add_u32_e32 v2, 8, v0
	s_nop 0
	v_cndmask_b32_e32 v51, v169, v51, vcc
	v_cmp_le_i32_e32 vcc, v2, v116
	v_add_u32_e32 v2, 9, v0
	s_nop 0
	v_cndmask_b32_e32 v52, v169, v52, vcc
	v_cmp_le_i32_e32 vcc, v2, v116
	v_add_u32_e32 v2, 10, v0
	s_nop 0
	v_cndmask_b32_e32 v53, v169, v53, vcc
	v_cmp_le_i32_e32 vcc, v2, v116
	v_add_u32_e32 v2, 11, v0
	s_nop 0
	v_cndmask_b32_e32 v54, v169, v54, vcc
	v_cmp_le_i32_e32 vcc, v2, v116
	v_add_u32_e32 v2, 16, v0
	s_nop 0
	v_cndmask_b32_e32 v55, v169, v55, vcc
	v_cmp_le_i32_e32 vcc, v2, v116
	v_add_u32_e32 v2, 17, v0
	s_nop 0
	v_cndmask_b32_e32 v56, v169, v56, vcc
	v_cmp_le_i32_e32 vcc, v2, v116
	v_add_u32_e32 v2, 18, v0
	s_nop 0
	v_cndmask_b32_e32 v57, v169, v57, vcc
	v_cmp_le_i32_e32 vcc, v2, v116
	v_add_u32_e32 v2, 19, v0
	s_nop 0
	v_cndmask_b32_e32 v58, v169, v58, vcc
	v_cmp_le_i32_e32 vcc, v2, v116
	v_add_u32_e32 v2, 24, v0
	s_nop 0
	v_cndmask_b32_e32 v59, v169, v59, vcc
	v_cmp_le_i32_e32 vcc, v2, v116
	v_add_u32_e32 v2, 25, v0
	s_nop 0
	v_cndmask_b32_e32 v60, v169, v60, vcc
	v_cmp_le_i32_e32 vcc, v2, v116
	v_add_u32_e32 v2, 26, v0
	s_nop 0
	v_cndmask_b32_e32 v61, v169, v61, vcc
	v_cmp_le_i32_e32 vcc, v2, v116
	v_add_u32_e32 v2, 27, v0
	s_nop 0
	v_cndmask_b32_e32 v62, v169, v62, vcc
	v_cmp_le_i32_e32 vcc, v2, v116
	v_add_u32_e32 v2, 32, v0
	s_nop 0
	v_cndmask_b32_e32 v63, v169, v63, vcc
	v_cmp_le_i32_e32 vcc, v2, v116
	v_add_u32_e32 v2, 33, v0
	s_nop 0
	v_cndmask_b32_e32 v64, v169, v64, vcc
	v_cmp_le_i32_e32 vcc, v2, v116
	v_add_u32_e32 v2, 34, v0
	s_nop 0
	v_cndmask_b32_e32 v65, v169, v65, vcc
	v_cmp_le_i32_e32 vcc, v2, v116
	v_add_u32_e32 v2, 35, v0
	s_nop 0
	v_cndmask_b32_e32 v66, v169, v66, vcc
	v_cmp_le_i32_e32 vcc, v2, v116
	v_add_u32_e32 v2, 40, v0
	s_nop 0
	v_cndmask_b32_e32 v67, v169, v67, vcc
	v_cmp_le_i32_e32 vcc, v2, v116
	v_add_u32_e32 v2, 41, v0
	s_nop 0
	v_cndmask_b32_e32 v68, v169, v68, vcc
	v_cmp_le_i32_e32 vcc, v2, v116
	v_add_u32_e32 v2, 42, v0
	s_nop 0
	v_cndmask_b32_e32 v69, v169, v69, vcc
	v_cmp_le_i32_e32 vcc, v2, v116
	v_add_u32_e32 v2, 43, v0
	s_nop 0
	v_cndmask_b32_e32 v70, v169, v70, vcc
	v_cmp_le_i32_e32 vcc, v2, v116
	v_add_u32_e32 v2, 48, v0
	s_nop 0
	v_cndmask_b32_e32 v71, v169, v71, vcc
	v_cmp_le_i32_e32 vcc, v2, v116
	v_add_u32_e32 v2, 49, v0
	s_nop 0
	v_cndmask_b32_e32 v72, v169, v72, vcc
	v_cmp_le_i32_e32 vcc, v2, v116
	v_add_u32_e32 v2, 50, v0
	s_nop 0
	v_cndmask_b32_e32 v73, v169, v73, vcc
	v_cmp_le_i32_e32 vcc, v2, v116
	v_add_u32_e32 v2, 51, v0
	s_nop 0
	v_cndmask_b32_e32 v74, v169, v74, vcc
	v_cmp_le_i32_e32 vcc, v2, v116
	v_add_u32_e32 v2, 56, v0
	s_nop 0
	v_cndmask_b32_e32 v75, v169, v75, vcc
	v_cmp_le_i32_e32 vcc, v2, v116
	v_add_u32_e32 v2, 57, v0
	s_nop 0
	v_cndmask_b32_e32 v76, v169, v76, vcc
	v_cmp_le_i32_e32 vcc, v2, v116
	v_add_u32_e32 v2, 58, v0
	v_add_u32_e32 v0, 59, v0
	v_cndmask_b32_e32 v77, v169, v77, vcc
	v_cmp_le_i32_e32 vcc, v2, v116
	s_nop 1
	v_cndmask_b32_e32 v78, v169, v78, vcc
	v_cmp_gt_i32_e32 vcc, v0, v116
	s_and_saveexec_b64 s[0:1], vcc
	v_mov_b32_e32 v79, 0xf149f2ca
	s_or_b64 exec, exec, s[0:1]

.LBB0_700:
	s_mul_i32 s14, s0, 0x4a00
	v_add_u32_e32 v0, s14, v148
	v_add3_u32 v0, v0, v130, v132
	s_cmp_gt_i32 s7, s5
	s_waitcnt lgkmcnt(0)
	s_barrier
	s_cbranch_scc1 .Ld4_inactive
	ds_read_b128 v[2:5], v0
	ds_read_b128 v[236:239], v0 offset:4608
	ds_read_b128 v[240:243], v0 offset:32
	ds_read_b128 v[244:247], v0 offset:4640
	s_add_i32 s0, s7, 63
	v_cmp_le_i32_e32 vcc, s0, v128
	s_cmp_eq_u64 vcc, exec
	s_waitcnt lgkmcnt(3)
	v_mfma_f32_32x32x16_bf16 v[80:95], v[2:5], v[96:99], v[48:63]
	s_waitcnt lgkmcnt(2)
	v_mfma_f32_32x32x16_bf16 v[64:79], v[236:239], v[96:99], v[48:63]
	s_waitcnt lgkmcnt(1)
	v_mfma_f32_32x32x16_bf16 v[80:95], v[240:243], v[100:103], v[80:95]
	s_waitcnt lgkmcnt(0)
	v_mfma_f32_32x32x16_bf16 v[64:79], v[244:247], v[100:103], v[64:79]
	s_cbranch_scc1 .LBB0_705
	v_add_u32_e32 v0, s7, v125
	v_cmp_lt_i32_e32 vcc, v0, v128
	v_add_u32_e32 v2, 2, v0
	s_nop 4
	v_cndmask_b32_e32 v81, v169, v81, vcc
	v_cmp_le_i32_e32 vcc, v0, v128
	s_nop 1
	v_cndmask_b32_e32 v80, v169, v80, vcc
	v_cmp_le_i32_e32 vcc, v2, v128
	v_add_u32_e32 v2, 3, v0
	s_nop 0
	v_cndmask_b32_e32 v82, v169, v82, vcc
	v_cmp_le_i32_e32 vcc, v2, v128
	v_add_u32_e32 v2, 8, v0
	s_nop 0
	v_cndmask_b32_e32 v83, v169, v83, vcc
	v_cmp_le_i32_e32 vcc, v2, v128
	v_add_u32_e32 v2, 9, v0
	s_nop 0
	v_cndmask_b32_e32 v84, v169, v84, vcc
	v_cmp_le_i32_e32 vcc, v2, v128
	v_add_u32_e32 v2, 10, v0
	s_nop 0
	v_cndmask_b32_e32 v85, v169, v85, vcc
	v_cmp_le_i32_e32 vcc, v2, v128
	v_add_u32_e32 v2, 11, v0
	s_nop 0
	v_cndmask_b32_e32 v86, v169, v86, vcc
	v_cmp_le_i32_e32 vcc, v2, v128
	v_add_u32_e32 v2, 16, v0
	s_nop 0
	v_cndmask_b32_e32 v87, v169, v87, vcc
	v_cmp_le_i32_e32 vcc, v2, v128
	v_add_u32_e32 v2, 17, v0
	s_nop 0
	v_cndmask_b32_e32 v88, v169, v88, vcc
	v_cmp_le_i32_e32 vcc, v2, v128
	v_add_u32_e32 v2, 18, v0
	s_nop 0
	v_cndmask_b32_e32 v89, v169, v89, vcc
	v_cmp_le_i32_e32 vcc, v2, v128
	v_add_u32_e32 v2, 19, v0
	s_nop 0
	v_cndmask_b32_e32 v90, v169, v90, vcc
	v_cmp_le_i32_e32 vcc, v2, v128
	v_add_u32_e32 v2, 24, v0
	s_nop 0
	v_cndmask_b32_e32 v91, v169, v91, vcc
	v_cmp_le_i32_e32 vcc, v2, v128
	v_add_u32_e32 v2, 25, v0
	s_nop 0
	v_cndmask_b32_e32 v92, v169, v92, vcc
	v_cmp_le_i32_e32 vcc, v2, v128
	v_add_u32_e32 v2, 26, v0
	s_nop 0
	v_cndmask_b32_e32 v93, v169, v93, vcc
	v_cmp_le_i32_e32 vcc, v2, v128
	v_add_u32_e32 v2, 27, v0
	s_nop 0
	v_cndmask_b32_e32 v94, v169, v94, vcc
	v_cmp_le_i32_e32 vcc, v2, v128
	v_add_u32_e32 v2, 32, v0
	s_nop 0
	v_cndmask_b32_e32 v95, v169, v95, vcc
	v_cmp_le_i32_e32 vcc, v2, v128
	v_add_u32_e32 v2, 33, v0
	s_nop 0
	v_cndmask_b32_e32 v64, v169, v64, vcc
	v_cmp_le_i32_e32 vcc, v2, v128
	v_add_u32_e32 v2, 34, v0
	s_nop 0
	v_cndmask_b32_e32 v65, v169, v65, vcc
	v_cmp_le_i32_e32 vcc, v2, v128
	v_add_u32_e32 v2, 35, v0
	s_nop 0
	v_cndmask_b32_e32 v66, v169, v66, vcc
	v_cmp_le_i32_e32 vcc, v2, v128
	v_add_u32_e32 v2, 40, v0
	s_nop 0
	v_cndmask_b32_e32 v67, v169, v67, vcc
	v_cmp_le_i32_e32 vcc, v2, v128
	v_add_u32_e32 v2, 41, v0
	s_nop 0
	v_cndmask_b32_e32 v68, v169, v68, vcc
	v_cmp_le_i32_e32 vcc, v2, v128
	v_add_u32_e32 v2, 42, v0
	s_nop 0
	v_cndmask_b32_e32 v69, v169, v69, vcc
	v_cmp_le_i32_e32 vcc, v2, v128
	v_add_u32_e32 v2, 43, v0
	s_nop 0
	v_cndmask_b32_e32 v70, v169, v70, vcc
	v_cmp_le_i32_e32 vcc, v2, v128
	v_add_u32_e32 v2, 48, v0
	s_nop 0
	v_cndmask_b32_e32 v71, v169, v71, vcc
	v_cmp_le_i32_e32 vcc, v2, v128
	v_add_u32_e32 v2, 49, v0
	s_nop 0
	v_cndmask_b32_e32 v72, v169, v72, vcc
	v_cmp_le_i32_e32 vcc, v2, v128
	v_add_u32_e32 v2, 50, v0
	s_nop 0
	v_cndmask_b32_e32 v73, v169, v73, vcc
	v_cmp_le_i32_e32 vcc, v2, v128
	v_add_u32_e32 v2, 51, v0
	s_nop 0
	v_cndmask_b32_e32 v74, v169, v74, vcc
	v_cmp_le_i32_e32 vcc, v2, v128
	v_add_u32_e32 v2, 56, v0
	s_nop 0
	v_cndmask_b32_e32 v75, v169, v75, vcc
	v_cmp_le_i32_e32 vcc, v2, v128
	v_add_u32_e32 v2, 57, v0
	s_nop 0
	v_cndmask_b32_e32 v76, v169, v76, vcc
	v_cmp_le_i32_e32 vcc, v2, v128
	v_add_u32_e32 v2, 58, v0
	v_add_u32_e32 v0, 59, v0
	v_cndmask_b32_e32 v77, v169, v77, vcc
	v_cmp_le_i32_e32 vcc, v2, v128
	s_nop 1
	v_cndmask_b32_e32 v78, v169, v78, vcc
	v_cmp_gt_i32_e32 vcc, v0, v128
	s_and_saveexec_b64 s[0:1], vcc
	v_mov_b32_e32 v79, 0xf149f2ca
	s_or_b64 exec, exec, s[0:1]

.LBB0_909:
	s_mul_i32 s22, s0, 0x4a00
	v_add3_u32 v193, s22, v182, v130
	s_cmp_gt_i32 s15, s14
	s_waitcnt lgkmcnt(0)
	s_barrier
	s_cbranch_scc1 .Ld5s_inactive
	s_lshr_b32 s1, s16, 3
	s_and_b32 s1, s1, 0x1ffffffc
	v_add_u32_e32 v50, s1, v114
	ds_read_b32 v50, v50
	s_and_b32 s1, s16, 31
	s_waitcnt lgkmcnt(0)
	v_bfe_u32 v51, v50, s1, 1
	v_cmp_ne_u32_e32 vcc, 0, v51
	s_cbranch_vccz .Ld5s_inactive
	v_lshrrev_b32_e32 v147, s1, v50
	ds_read_b128 v[148:151], v193 offset:4608
	ds_read_b128 v[50:53], v193
	ds_read_b128 v[152:155], v193 offset:32
	ds_read_b128 v[236:239], v193 offset:4640
	ds_read_b128 v[240:243], v193 offset:64
	ds_read_b128 v[244:247], v193 offset:4672
	ds_read_b128 v[248:251], v193 offset:96
	s_add_i32 s23, s15, 63
	v_cmp_le_i32_e32 vcc, s23, v128
	s_waitcnt lgkmcnt(5)
	v_mfma_f32_32x32x16_bf16 v[66:81], v[50:53], v[82:85], v[34:49]
	s_waitcnt lgkmcnt(4)
	v_mfma_f32_32x32x16_bf16 v[66:81], v[152:155], v[86:89], v[66:81]
	ds_read_b128 v[152:155], v193 offset:4704
	v_and_b32_e32 v147, 1, v147
	s_cmp_lg_u64 vcc, exec
	s_mov_b64 s[0:1], -1
	v_cmp_eq_u32_e32 vcc, 1, v147
	s_mov_b64 s[4:5], -1
	v_mfma_f32_32x32x16_bf16 v[50:65], v[148:151], v[82:85], v[34:49]
	s_waitcnt lgkmcnt(4)
	v_mfma_f32_32x32x16_bf16 v[50:65], v[236:239], v[86:89], v[50:65]
	s_waitcnt lgkmcnt(3)
	v_mfma_f32_32x32x16_bf16 v[66:81], v[240:243], v[90:93], v[66:81]
	s_waitcnt lgkmcnt(2)
	v_mfma_f32_32x32x16_bf16 v[50:65], v[244:247], v[90:93], v[50:65]
	s_waitcnt lgkmcnt(1)
	v_mfma_f32_32x32x16_bf16 v[66:81], v[248:251], v[94:97], v[66:81]
	s_waitcnt lgkmcnt(0)
	v_mfma_f32_32x32x16_bf16 v[50:65], v[152:155], v[94:97], v[50:65]
	s_cbranch_scc0 .LBB0_917
	v_cndmask_b32_e32 v148, -1, v128, vcc
	v_cmp_le_i32_e32 vcc, s23, v148
	s_cmp_eq_u64 vcc, exec
	s_cbranch_scc1 .LBB0_916
	v_add_u32_e32 v149, s15, v125
	v_cmp_lt_i32_e32 vcc, v149, v148
	v_add_u32_e32 v150, 2, v149
	s_nop 2
	v_cndmask_b32_e32 v67, v169, v67, vcc
	v_cmp_le_i32_e32 vcc, v149, v148
	s_nop 1
	v_cndmask_b32_e32 v66, v169, v66, vcc
	v_cmp_le_i32_e32 vcc, v150, v148
	v_add_u32_e32 v150, 3, v149
	s_nop 0
	v_cndmask_b32_e32 v68, v169, v68, vcc
	v_cmp_le_i32_e32 vcc, v150, v148
	v_add_u32_e32 v150, 8, v149
	s_nop 0
	v_cndmask_b32_e32 v69, v169, v69, vcc
	v_cmp_le_i32_e32 vcc, v150, v148
	v_add_u32_e32 v150, 9, v149
	s_nop 0
	v_cndmask_b32_e32 v70, v169, v70, vcc
	v_cmp_le_i32_e32 vcc, v150, v148
	v_add_u32_e32 v150, 10, v149
	s_nop 0
	v_cndmask_b32_e32 v71, v169, v71, vcc
	v_cmp_le_i32_e32 vcc, v150, v148
	v_add_u32_e32 v150, 11, v149
	s_nop 0
	v_cndmask_b32_e32 v72, v169, v72, vcc
	v_cmp_le_i32_e32 vcc, v150, v148
	v_add_u32_e32 v150, 16, v149
	s_nop 0
	v_cndmask_b32_e32 v73, v169, v73, vcc
	v_cmp_le_i32_e32 vcc, v150, v148
	v_add_u32_e32 v150, 17, v149
	s_nop 0
	v_cndmask_b32_e32 v74, v169, v74, vcc
	v_cmp_le_i32_e32 vcc, v150, v148
	v_add_u32_e32 v150, 18, v149
	s_nop 0
	v_cndmask_b32_e32 v75, v169, v75, vcc
	v_cmp_le_i32_e32 vcc, v150, v148
	v_add_u32_e32 v150, 19, v149
	s_nop 0
	v_cndmask_b32_e32 v76, v169, v76, vcc
	v_cmp_le_i32_e32 vcc, v150, v148
	v_add_u32_e32 v150, 24, v149
	s_nop 0
	v_cndmask_b32_e32 v77, v169, v77, vcc
	v_cmp_le_i32_e32 vcc, v150, v148
	v_add_u32_e32 v150, 25, v149
	s_nop 0
	v_cndmask_b32_e32 v78, v169, v78, vcc
	v_cmp_le_i32_e32 vcc, v150, v148
	v_add_u32_e32 v150, 26, v149
	s_nop 0
	v_cndmask_b32_e32 v79, v169, v79, vcc
	v_cmp_le_i32_e32 vcc, v150, v148
	v_add_u32_e32 v150, 27, v149
	s_nop 0
	v_cndmask_b32_e32 v80, v169, v80, vcc
	v_cmp_le_i32_e32 vcc, v150, v148
	v_add_u32_e32 v150, 32, v149
	s_nop 0
	v_cndmask_b32_e32 v81, v169, v81, vcc
	v_cmp_le_i32_e32 vcc, v150, v148
	v_add_u32_e32 v150, 33, v149
	s_nop 0
	v_cndmask_b32_e32 v50, v169, v50, vcc
	v_cmp_le_i32_e32 vcc, v150, v148
	v_add_u32_e32 v150, 34, v149
	s_nop 0
	v_cndmask_b32_e32 v51, v169, v51, vcc
	v_cmp_le_i32_e32 vcc, v150, v148
	v_add_u32_e32 v150, 35, v149
	s_nop 0
	v_cndmask_b32_e32 v52, v169, v52, vcc
	v_cmp_le_i32_e32 vcc, v150, v148
	v_add_u32_e32 v150, 40, v149
	s_nop 0
	v_cndmask_b32_e32 v53, v169, v53, vcc
	v_cmp_le_i32_e32 vcc, v150, v148
	v_add_u32_e32 v150, 41, v149
	s_nop 0
	v_cndmask_b32_e32 v54, v169, v54, vcc
	v_cmp_le_i32_e32 vcc, v150, v148
	v_add_u32_e32 v150, 42, v149
	s_nop 0
	v_cndmask_b32_e32 v55, v169, v55, vcc
	v_cmp_le_i32_e32 vcc, v150, v148
	v_add_u32_e32 v150, 43, v149
	s_nop 0
	v_cndmask_b32_e32 v56, v169, v56, vcc
	v_cmp_le_i32_e32 vcc, v150, v148
	v_add_u32_e32 v150, 48, v149
	s_nop 0
	v_cndmask_b32_e32 v57, v169, v57, vcc
	v_cmp_le_i32_e32 vcc, v150, v148
	v_add_u32_e32 v150, 49, v149
	s_nop 0
	v_cndmask_b32_e32 v58, v169, v58, vcc
	v_cmp_le_i32_e32 vcc, v150, v148
	v_add_u32_e32 v150, 50, v149
	s_nop 0
	v_cndmask_b32_e32 v59, v169, v59, vcc
	v_cmp_le_i32_e32 vcc, v150, v148
	v_add_u32_e32 v150, 51, v149
	s_nop 0
	v_cndmask_b32_e32 v60, v169, v60, vcc
	v_cmp_le_i32_e32 vcc, v150, v148
	v_add_u32_e32 v150, 56, v149
	s_nop 0
	v_cndmask_b32_e32 v61, v169, v61, vcc
	v_cmp_le_i32_e32 vcc, v150, v148
	v_add_u32_e32 v150, 57, v149
	s_nop 0
	v_cndmask_b32_e32 v62, v169, v62, vcc
	v_cmp_le_i32_e32 vcc, v150, v148
	v_add_u32_e32 v150, 58, v149
	v_add_u32_e32 v149, 59, v149
	v_cndmask_b32_e32 v63, v169, v63, vcc
	v_cmp_le_i32_e32 vcc, v150, v148
	s_nop 1
	v_cndmask_b32_e32 v64, v169, v64, vcc
	v_cmp_gt_i32_e32 vcc, v149, v148
	s_and_saveexec_b64 s[4:5], vcc
	v_mov_b32_e32 v65, 0xf149f2ca
	s_or_b64 exec, exec, s[4:5]

.LBB0_931:
	s_cmp_le_i32 s14, s7
	s_cselect_b64 s[16:17], -1, 0
	s_add_i32 s1, s14, 63
	s_cmp_ge_i32 s1, s9
	s_cselect_b64 s[22:23], -1, 0
	s_and_b64 s[16:17], s[16:17], s[22:23]
	s_andn2_b64 vcc, exec, s[16:17]
	s_mul_i32 s16, s0, 0x4a00
	v_add3_u32 v142, s16, v182, v130
	s_waitcnt lgkmcnt(0)
	s_barrier
	s_cbranch_vccnz .Ld6_inactive
	ds_read_b128 v[50:53], v142
	ds_read_b128 v[138:141], v142 offset:4608
	ds_read_b128 v[236:239], v142 offset:32
	ds_read_b128 v[240:243], v142 offset:4640
	ds_read_b128 v[244:247], v142 offset:64
	ds_read_b128 v[248:251], v142 offset:4672
	v_cmp_le_i32_e32 vcc, s1, v128
	v_cmp_ge_i32_e64 s[0:1], s14, v137
	s_and_b64 s[0:1], vcc, s[0:1]
	s_waitcnt lgkmcnt(5)
	v_mfma_f32_32x32x16_bf16 v[66:81], v[50:53], v[82:85], v[34:49]
	s_waitcnt lgkmcnt(4)
	v_mfma_f32_32x32x16_bf16 v[50:65], v[138:141], v[82:85], v[34:49]
	ds_read_b128 v[138:141], v142 offset:96
	s_waitcnt lgkmcnt(4)
	v_mfma_f32_32x32x16_bf16 v[66:81], v[236:239], v[86:89], v[66:81]
	ds_read_b128 v[236:239], v142 offset:4704
	s_waitcnt lgkmcnt(4)
	v_mfma_f32_32x32x16_bf16 v[50:65], v[240:243], v[86:89], v[50:65]
	s_waitcnt lgkmcnt(3)
	v_mfma_f32_32x32x16_bf16 v[66:81], v[244:247], v[90:93], v[66:81]
	s_waitcnt lgkmcnt(2)
	v_mfma_f32_32x32x16_bf16 v[50:65], v[248:251], v[90:93], v[50:65]
	s_waitcnt lgkmcnt(1)
	v_mfma_f32_32x32x16_bf16 v[66:81], v[138:141], v[94:97], v[66:81]
	v_cndmask_b32_e64 v142, 0, 1, s[0:1]
	v_cmp_ne_u32_e32 vcc, 0, v142
	s_cmp_eq_u64 vcc, exec
	s_waitcnt lgkmcnt(0)
	v_mfma_f32_32x32x16_bf16 v[50:65], v[236:239], v[94:97], v[50:65]
	s_cbranch_scc1 .LBB0_936
	v_add_u32_e32 v138, s14, v125
	v_cmp_gt_i32_e32 vcc, v138, v128
	v_cmp_lt_i32_e64 s[0:1], v138, v137
	s_or_b64 vcc, vcc, s[0:1]
	v_add_u32_e32 v139, 1, v138
	v_cndmask_b32_e32 v66, v66, v169, vcc
	v_cmp_ge_i32_e32 vcc, v138, v128
	v_cmp_lt_i32_e64 s[0:1], v139, v137
	s_or_b64 vcc, vcc, s[0:1]
	v_add_u32_e32 v139, 2, v138
	v_cndmask_b32_e32 v67, v67, v169, vcc
	v_cmp_gt_i32_e32 vcc, v139, v128
	v_cmp_lt_i32_e64 s[0:1], v139, v137
	s_or_b64 vcc, vcc, s[0:1]
	v_add_u32_e32 v139, 3, v138
	v_cndmask_b32_e32 v68, v68, v169, vcc
	v_cmp_gt_i32_e32 vcc, v139, v128
	v_cmp_lt_i32_e64 s[0:1], v139, v137
	s_or_b64 vcc, vcc, s[0:1]
	v_add_u32_e32 v139, 8, v138
	v_cndmask_b32_e32 v69, v69, v169, vcc
	v_cmp_gt_i32_e32 vcc, v139, v128
	v_cmp_lt_i32_e64 s[0:1], v139, v137
	s_or_b64 vcc, vcc, s[0:1]
	v_add_u32_e32 v139, 9, v138
	v_cndmask_b32_e32 v70, v70, v169, vcc
	v_cmp_gt_i32_e32 vcc, v139, v128
	v_cmp_lt_i32_e64 s[0:1], v139, v137
	s_or_b64 vcc, vcc, s[0:1]
	v_add_u32_e32 v139, 10, v138
	v_cndmask_b32_e32 v71, v71, v169, vcc
	v_cmp_gt_i32_e32 vcc, v139, v128
	v_cmp_lt_i32_e64 s[0:1], v139, v137
	s_or_b64 vcc, vcc, s[0:1]
	v_add_u32_e32 v139, 11, v138
	v_cndmask_b32_e32 v72, v72, v169, vcc
	v_cmp_gt_i32_e32 vcc, v139, v128
	v_cmp_lt_i32_e64 s[0:1], v139, v137
	s_or_b64 vcc, vcc, s[0:1]
	v_add_u32_e32 v139, 16, v138
	v_cndmask_b32_e32 v73, v73, v169, vcc
	v_cmp_gt_i32_e32 vcc, v139, v128
	v_cmp_lt_i32_e64 s[0:1], v139, v137
	s_or_b64 vcc, vcc, s[0:1]
	v_add_u32_e32 v139, 17, v138
	v_cndmask_b32_e32 v74, v74, v169, vcc
	v_cmp_gt_i32_e32 vcc, v139, v128
	v_cmp_lt_i32_e64 s[0:1], v139, v137
	s_or_b64 vcc, vcc, s[0:1]
	v_add_u32_e32 v139, 18, v138
	v_cndmask_b32_e32 v75, v75, v169, vcc
	v_cmp_gt_i32_e32 vcc, v139, v128
	v_cmp_lt_i32_e64 s[0:1], v139, v137
	s_or_b64 vcc, vcc, s[0:1]
	v_add_u32_e32 v139, 19, v138
	v_cndmask_b32_e32 v76, v76, v169, vcc
	v_cmp_gt_i32_e32 vcc, v139, v128
	v_cmp_lt_i32_e64 s[0:1], v139, v137
	s_or_b64 vcc, vcc, s[0:1]
	v_add_u32_e32 v139, 24, v138
	v_cndmask_b32_e32 v77, v77, v169, vcc
	v_cmp_gt_i32_e32 vcc, v139, v128
	v_cmp_lt_i32_e64 s[0:1], v139, v137
	s_or_b64 vcc, vcc, s[0:1]
	v_add_u32_e32 v139, 25, v138
	v_cndmask_b32_e32 v78, v78, v169, vcc
	v_cmp_gt_i32_e32 vcc, v139, v128
	v_cmp_lt_i32_e64 s[0:1], v139, v137
	s_or_b64 vcc, vcc, s[0:1]
	v_add_u32_e32 v139, 26, v138
	v_cndmask_b32_e32 v79, v79, v169, vcc
	v_cmp_gt_i32_e32 vcc, v139, v128
	v_cmp_lt_i32_e64 s[0:1], v139, v137
	s_or_b64 vcc, vcc, s[0:1]
	v_add_u32_e32 v139, 27, v138
	v_cndmask_b32_e32 v80, v80, v169, vcc
	v_cmp_gt_i32_e32 vcc, v139, v128
	v_cmp_lt_i32_e64 s[0:1], v139, v137
	s_or_b64 vcc, vcc, s[0:1]
	v_add_u32_e32 v139, 32, v138
	v_cndmask_b32_e32 v81, v81, v169, vcc
	v_cmp_gt_i32_e32 vcc, v139, v128
	v_cmp_lt_i32_e64 s[0:1], v139, v137
	s_or_b64 vcc, vcc, s[0:1]
	v_add_u32_e32 v139, 33, v138
	v_cndmask_b32_e32 v50, v50, v169, vcc
	v_cmp_gt_i32_e32 vcc, v139, v128
	v_cmp_lt_i32_e64 s[0:1], v139, v137
	s_or_b64 vcc, vcc, s[0:1]
	v_add_u32_e32 v139, 34, v138
	v_cndmask_b32_e32 v51, v51, v169, vcc
	v_cmp_gt_i32_e32 vcc, v139, v128
	v_cmp_lt_i32_e64 s[0:1], v139, v137
	s_or_b64 vcc, vcc, s[0:1]
	v_add_u32_e32 v139, 35, v138
	v_cndmask_b32_e32 v52, v52, v169, vcc
	v_cmp_gt_i32_e32 vcc, v139, v128
	v_cmp_lt_i32_e64 s[0:1], v139, v137
	s_or_b64 vcc, vcc, s[0:1]
	v_add_u32_e32 v139, 40, v138
	v_cndmask_b32_e32 v53, v53, v169, vcc
	v_cmp_gt_i32_e32 vcc, v139, v128
	v_cmp_lt_i32_e64 s[0:1], v139, v137
	s_or_b64 vcc, vcc, s[0:1]
	v_add_u32_e32 v139, 41, v138
	v_cndmask_b32_e32 v54, v54, v169, vcc
	v_cmp_gt_i32_e32 vcc, v139, v128
	v_cmp_lt_i32_e64 s[0:1], v139, v137
	s_or_b64 vcc, vcc, s[0:1]
	v_add_u32_e32 v139, 42, v138
	v_cndmask_b32_e32 v55, v55, v169, vcc
	v_cmp_gt_i32_e32 vcc, v139, v128
	v_cmp_lt_i32_e64 s[0:1], v139, v137
	s_or_b64 vcc, vcc, s[0:1]
	v_add_u32_e32 v139, 43, v138
	v_cndmask_b32_e32 v56, v56, v169, vcc
	v_cmp_gt_i32_e32 vcc, v139, v128
	v_cmp_lt_i32_e64 s[0:1], v139, v137
	s_or_b64 vcc, vcc, s[0:1]
	v_add_u32_e32 v139, 48, v138
	v_cndmask_b32_e32 v57, v57, v169, vcc
	v_cmp_gt_i32_e32 vcc, v139, v128
	v_cmp_lt_i32_e64 s[0:1], v139, v137
	s_or_b64 vcc, vcc, s[0:1]
	v_add_u32_e32 v139, 49, v138
	v_cndmask_b32_e32 v58, v58, v169, vcc
	v_cmp_gt_i32_e32 vcc, v139, v128
	v_cmp_lt_i32_e64 s[0:1], v139, v137
	s_or_b64 vcc, vcc, s[0:1]
	v_add_u32_e32 v139, 50, v138
	v_cndmask_b32_e32 v59, v59, v169, vcc
	v_cmp_gt_i32_e32 vcc, v139, v128
	v_cmp_lt_i32_e64 s[0:1], v139, v137
	s_or_b64 vcc, vcc, s[0:1]
	v_add_u32_e32 v139, 51, v138
	v_cndmask_b32_e32 v60, v60, v169, vcc
	v_cmp_gt_i32_e32 vcc, v139, v128
	v_cmp_lt_i32_e64 s[0:1], v139, v137
	s_or_b64 vcc, vcc, s[0:1]
	v_add_u32_e32 v139, 56, v138
	v_cndmask_b32_e32 v61, v61, v169, vcc
	v_cmp_gt_i32_e32 vcc, v139, v128
	v_cmp_lt_i32_e64 s[0:1], v139, v137
	s_or_b64 vcc, vcc, s[0:1]
	v_add_u32_e32 v139, 57, v138
	v_cndmask_b32_e32 v62, v62, v169, vcc
	v_cmp_gt_i32_e32 vcc, v139, v128
	v_cmp_lt_i32_e64 s[0:1], v139, v137
	s_or_b64 vcc, vcc, s[0:1]
	v_add_u32_e32 v139, 58, v138
	v_cndmask_b32_e32 v63, v63, v169, vcc
	v_cmp_gt_i32_e32 vcc, v139, v128
	v_cmp_lt_i32_e64 s[0:1], v139, v137
	s_or_b64 vcc, vcc, s[0:1]
	v_add_u32_e32 v138, 59, v138
	v_cndmask_b32_e32 v64, v64, v169, vcc
	v_cmp_gt_i32_e32 vcc, v138, v128
	v_cmp_lt_i32_e64 s[0:1], v138, v137
	s_or_b64 s[22:23], vcc, s[0:1]
	s_and_saveexec_b64 s[0:1], s[22:23]
	v_mov_b32_e32 v65, 0xf149f2ca
	s_or_b64 exec, exec, s[0:1]
